# P0 rmsnorm rows: all of a row's loads issued before the first wait (the compiler had split them into three batches a memory latency apart)
# baseline (speedup 1.0000x reference)
; #define GAS __attribute__((address_space(1)))
; __device__ __forceinline__ void rms_row_to_bf16(const float* xrow, const float* g, bf16_t* orow, int lane) {
;     const GAS f32x4* xr = (const GAS f32x4*)xrow + lane;
;     f32x4 v[16], gv[16]; float s = 0.f;
;     const GAS f32x4* gr = (const GAS f32x4*)g + lane;
; #pragma unroll
;     for (int j = 0; j < 16; ++j) v[j] = __builtin_nontemporal_load(xr + 64 * j);
; #pragma unroll
;     for (int j = 0; j < 16; ++j) gv[j] = gr[64 * j];
; __device__ __forceinline__ void p0_prologue(Frame& F, bool all_weights) {
;     ...
;         else if (m < MT) rms_row_to_bf16(F.in[2] + (size_t)(m - MP) * DM, F.in[7], H + (size_t)m * DM, F.lane);
.LBB0_49:
	s_andn2_b64 vcc, exec, s[4:5]
	s_cbranch_vccnz .LBB0_51
	s_add_i32 s16, s40, 0xffffe000
	s_lshl_b64 s[4:5], s[16:17], 14
	v_lshl_add_u64 v[2:3], v[150:151], 0, s[4:5]
	global_load_dwordx4 v[78:81], v[2:3], off nt
	global_load_dwordx4 v[70:73], v[2:3], off offset:1024 nt
	global_load_dwordx4 v[62:65], v[2:3], off offset:2048 nt
	global_load_dwordx4 v[54:57], v[2:3], off offset:3072 nt
	v_add_co_u32_e32 v4, vcc, 0x1000, v2
	s_mov_b32 s7, s17
	s_nop 0
	v_addc_co_u32_e32 v5, vcc, 0, v3, vcc
	global_load_dwordx4 v[50:53], v[4:5], off nt
	global_load_dwordx4 v[42:45], v[4:5], off offset:1024 nt
	global_load_dwordx4 v[38:41], v[4:5], off offset:2048 nt
	global_load_dwordx4 v[34:37], v[4:5], off offset:3072 nt
	v_add_co_u32_e32 v4, vcc, 0x2000, v2
	s_nop 1

; #define GAS __attribute__((address_space(1)))
; __device__ __forceinline__ void rms_row_to_bf16(const float* xrow, const float* g, bf16_t* orow, int lane) {
;     const GAS f32x4* xr = (const GAS f32x4*)xrow + lane;
;     f32x4 v[16], gv[16]; float s = 0.f;
;     const GAS f32x4* gr = (const GAS f32x4*)g + lane;
; #pragma unroll
;     for (int j = 0; j < 16; ++j) v[j] = __builtin_nontemporal_load(xr + 64 * j);
; #pragma unroll
;     for (int j = 0; j < 16; ++j) gv[j] = gr[64 * j];
; #pragma unroll
;     for (int j = 0; j < 16; ++j) s += (v[j].x * v[j].x + v[j].y * v[j].y) + (v[j].z * v[j].z + v[j].w * v[j].w);
;     const float rstd = 1.0f / sqrtf(wave_sum(s) * (1.0f / DM) + EPS);
	v_addc_co_u32_e32 v5, vcc, 0, v3, vcc
	global_load_dwordx4 v[30:33], v[4:5], off nt
	global_load_dwordx4 v[26:29], v[4:5], off offset:1024 nt
	global_load_dwordx4 v[18:21], v[4:5], off offset:2048 nt
	global_load_dwordx4 v[162:165], v[120:121], off
	global_load_dwordx4 v[90:93], v[120:121], off offset:1024
	global_load_dwordx4 v[22:25], v[4:5], off offset:3072 nt
	v_add_co_u32_e32 v2, vcc, 0x3000, v2
	s_nop 0
	s_nop 0
	v_addc_co_u32_e32 v3, vcc, 0, v3, vcc
	global_load_dwordx4 v[14:17], v[2:3], off nt
	global_load_dwordx4 v[86:89], v[120:121], off offset:2048
	global_load_dwordx4 v[82:85], v[120:121], off offset:3072
	global_load_dwordx4 v[74:77], v[122:123], off
	global_load_dwordx4 v[66:69], v[124:125], off
	global_load_dwordx4 v[58:61], v[126:127], off
	global_load_dwordx4 v[46:49], v[128:129], off
	global_load_dwordx4 v[10:13], v[2:3], off offset:1024 nt
	global_load_dwordx4 v[6:9], v[2:3], off offset:2048 nt
	s_nop 0
	global_load_dwordx4 v[2:5], v[2:3], off offset:3072 nt
	s_waitcnt vmcnt(23)
	v_mul_f32_e32 v158, v79, v79
	v_mul_f32_e32 v159, v81, v81
	s_waitcnt vmcnt(22)
	v_mul_f32_e32 v166, v71, v71
	v_mul_f32_e32 v167, v73, v73
	s_waitcnt vmcnt(21)
	v_mul_f32_e32 v168, v63, v63
	v_mul_f32_e32 v169, v65, v65
	v_fmac_f32_e32 v158, v78, v78
	v_fmac_f32_e32 v159, v80, v80
	v_fmac_f32_e32 v166, v70, v70
	v_fmac_f32_e32 v167, v72, v72
	s_waitcnt vmcnt(20)
	v_mul_f32_e32 v170, v55, v55
	v_mul_f32_e32 v171, v57, v57
	v_fmac_f32_e32 v168, v62, v62
	v_fmac_f32_e32 v169, v64, v64
	v_add_f32_e32 v158, v158, v159
	v_add_f32_e32 v159, v166, v167
	v_fmac_f32_e32 v170, v54, v54
	v_fmac_f32_e32 v171, v56, v56
	v_add_f32_e32 v166, v168, v169
	s_waitcnt vmcnt(19)
	v_mul_f32_e32 v168, v51, v51
	v_mul_f32_e32 v169, v53, v53
	v_add_f32_e32 v158, v158, v159
	v_add_f32_e32 v167, v170, v171
	s_waitcnt vmcnt(18)
	v_mul_f32_e32 v170, v43, v43
	v_mul_f32_e32 v171, v45, v45
	v_fmac_f32_e32 v168, v50, v50
	v_fmac_f32_e32 v169, v52, v52
	v_add_f32_e32 v158, v158, v166
	s_waitcnt vmcnt(17)
	v_mul_f32_e32 v172, v39, v39
	v_mul_f32_e32 v173, v41, v41
	v_fmac_f32_e32 v170, v42, v42
	v_fmac_f32_e32 v171, v44, v44
	v_add_f32_e32 v166, v168, v169
	v_add_f32_e32 v158, v158, v167
	s_waitcnt vmcnt(16)
	v_mul_f32_e32 v174, v35, v35
	v_mul_f32_e32 v175, v37, v37
	v_fmac_f32_e32 v172, v38, v38
	v_fmac_f32_e32 v173, v40, v40
	v_add_f32_e32 v168, v170, v171
	v_add_f32_e32 v158, v158, v166
	v_fmac_f32_e32 v174, v34, v34
	v_fmac_f32_e32 v175, v36, v36
	v_add_f32_e32 v169, v172, v173
	v_add_f32_e32 v158, v158, v168
	v_add_f32_e32 v170, v174, v175
	v_add_f32_e32 v158, v158, v169
	v_add_f32_e32 v158, v158, v170
	s_waitcnt vmcnt(15)
	v_mul_f32_e32 v159, v31, v31
	v_mul_f32_e32 v176, v33, v33
	v_fmac_f32_e32 v159, v30, v30
	v_fmac_f32_e32 v176, v32, v32
	v_add_f32_e32 v159, v159, v176
	v_add_f32_e32 v158, v158, v159
	s_waitcnt vmcnt(14)
	v_mul_f32_e32 v159, v27, v27
	v_mul_f32_e32 v166, v29, v29
	v_fmac_f32_e32 v159, v26, v26
	v_fmac_f32_e32 v166, v28, v28
	v_add_f32_e32 v159, v159, v166
	v_add_f32_e32 v158, v158, v159
	s_waitcnt vmcnt(13)
	v_mul_f32_e32 v159, v19, v19
	v_mul_f32_e32 v166, v21, v21
	v_fmac_f32_e32 v159, v18, v18
	v_fmac_f32_e32 v166, v20, v20
	v_add_f32_e32 v159, v159, v166
	v_add_f32_e32 v158, v158, v159
	s_waitcnt vmcnt(10)
	v_mul_f32_e32 v159, v23, v23
	v_mul_f32_e32 v166, v25, v25
	v_fmac_f32_e32 v159, v22, v22
	v_fmac_f32_e32 v166, v24, v24
	v_add_f32_e32 v159, v159, v166
	v_add_f32_e32 v158, v158, v159
	s_waitcnt vmcnt(9)
	v_mul_f32_e32 v159, v15, v15
	v_mul_f32_e32 v166, v17, v17
	v_fmac_f32_e32 v159, v14, v14
	v_fmac_f32_e32 v166, v16, v16
	v_add_f32_e32 v159, v159, v166
	v_add_f32_e32 v158, v158, v159
	s_waitcnt vmcnt(2)
	v_mul_f32_e32 v159, v11, v11
	v_mul_f32_e32 v166, v13, v13
	v_fmac_f32_e32 v159, v10, v10
	v_fmac_f32_e32 v166, v12, v12
	v_add_f32_e32 v159, v159, v166
	v_add_f32_e32 v158, v158, v159
	s_waitcnt vmcnt(1)
	v_mul_f32_e32 v159, v7, v7
	v_mul_f32_e32 v166, v9, v9
	v_fmac_f32_e32 v159, v6, v6
	v_fmac_f32_e32 v166, v8, v8
	v_add_f32_e32 v159, v159, v166
	v_add_f32_e32 v158, v158, v159
	s_waitcnt vmcnt(0)
	v_mul_f32_e32 v159, v3, v3
	v_mul_f32_e32 v166, v5, v5
	v_fmac_f32_e32 v159, v2, v2
	v_fmac_f32_e32 v166, v4, v4
	v_add_f32_e32 v159, v159, v166
	v_add_f32_e32 v158, v158, v159
	v_mov_b32_e32 v159, 0
	global_load_dwordx4 v[166:169], v[130:131], off
	global_load_dwordx4 v[170:173], v[132:133], off
	global_load_dwordx4 v[174:177], v[134:135], off
	global_load_dwordx4 v[178:181], v[136:137], off
	v_add_f32_dpp v158, v158, v158 quad_perm:[1,0,3,2] row_mask:0xf bank_mask:0xf bound_ctrl:1
	s_nop 1
	v_add_f32_dpp v158, v158, v158 quad_perm:[2,3,0,1] row_mask:0xf bank_mask:0xf bound_ctrl:1
	s_nop 1
	v_add_f32_dpp v158, v158, v158 row_half_mirror row_mask:0xf bank_mask:0xf bound_ctrl:1
	s_nop 1
	v_add_f32_dpp v158, v158, v158 row_mirror row_mask:0xf bank_mask:0xf bound_ctrl:1
	s_nop 1
	v_mov_b32_dpp v159, v158 row_bcast:15 row_mask:0xa bank_mask:0xf
	v_add_f32_e32 v158, v158, v159
	v_mov_b32_e32 v159, 0
	s_nop 1
	v_mov_b32_dpp v159, v158 row_bcast:31 row_mask:0xc bank_mask:0xf
	v_add_f32_e32 v158, v158, v159
	s_nop 0
	v_readlane_b32 s4, v158, 63
	s_nop 1
	v_fma_f32 v158, s4, v161, v1
	v_mul_f32_e32 v159, 0x4f800000, v158
	v_cmp_gt_f32_e32 vcc, s18, v158
	s_nop 1
	v_cndmask_b32_e32 v158, v158, v159, vcc
	v_sqrt_f32_e32 v159, v158
	s_nop 0
	v_add_u32_e32 v182, -1, v159
	v_fma_f32 v183, -v182, v159, v158
	v_cmp_ge_f32_e64 s[4:5], 0, v183
	v_add_u32_e32 v183, 1, v159
	s_nop 0
	v_cndmask_b32_e64 v182, v159, v182, s[4:5]
	v_fma_f32 v159, -v183, v159, v158
	v_cmp_lt_f32_e64 s[4:5], 0, v159
	s_nop 1
	v_cndmask_b32_e64 v159, v182, v183, s[4:5]
; #define GAS __attribute__((address_space(1)))
; __device__ __forceinline__ unsigned cvt_pk_bf16(float lo, float hi) { unsigned r; asm volatile("v_cvt_pk_bf16_f32 %0, %1, %2" : "=v"(r) : "v"(lo), "v"(hi)); return r; }
; __device__ __forceinline__ void rms_row_to_bf16(const float* xrow, const float* g, bf16_t* orow, int lane) {
;     ...
;     const float rstd = 1.0f / sqrtf(wave_sum(s) * (1.0f / DM) + EPS);
;     GAS u32x2* o8 = (GAS u32x2*)orow + lane;
; #pragma unroll
;     for (int j = 0; j < 16; ++j) { const f32x4 gg = gv[j]; u32x2 w; w.x = cvt_pk_bf16(v[j].x * rstd * gg.x, v[j].y * rstd * gg.y); w.y = cvt_pk_bf16(v[j].z * rstd * gg.z, v[j].w * rstd * gg.w); o8[64 * j] = w; }
	v_mul_f32_e32 v182, 0x37800000, v159
	v_cndmask_b32_e32 v159, v159, v182, vcc
	global_load_dwordx4 v[182:185], v[138:139], off
	global_load_dwordx4 v[186:189], v[140:141], off
	global_load_dwordx4 v[190:193], v[142:143], off
	global_load_dwordx4 v[194:197], v[144:145], off
	v_cmp_class_f32_e32 vcc, v158, v160
	s_nop 1
	v_cndmask_b32_e32 v158, v159, v158, vcc
	v_div_scale_f32 v159, s[4:5], v158, v158, 1.0
	v_rcp_f32_e32 v198, v159
	s_nop 0
	v_fma_f32 v199, -v159, v198, 1.0
	v_fmac_f32_e32 v198, v199, v198
	v_div_scale_f32 v199, vcc, 1.0, v158, 1.0
	v_mul_f32_e32 v200, v199, v198
	v_fma_f32 v201, -v159, v200, v199
	v_fmac_f32_e32 v200, v201, v198
	v_fma_f32 v159, -v159, v200, v199
	v_div_fmas_f32 v159, v159, v198, v200
	v_div_fixup_f32 v198, v159, v158, 1.0
	v_mul_f32_e32 v78, v78, v198
	v_mul_f32_e32 v79, v79, v198
	v_mul_f32_e32 v78, v162, v78
	v_mul_f32_e32 v79, v163, v79
	v_cvt_pk_bf16_f32 v78, v78, v79
	v_mul_f32_e32 v79, v80, v198
	v_mul_f32_e32 v70, v70, v198
	v_mul_f32_e32 v71, v71, v198
	v_lshl_add_u64 v[158:159], v[152:153], 0, s[6:7]
	v_mul_f32_e32 v79, v164, v79
	v_mul_f32_e32 v80, v81, v198
	v_mul_f32_e32 v70, v90, v70
	v_mul_f32_e32 v71, v91, v71
	v_mul_f32_e32 v80, v165, v80
	v_cvt_pk_bf16_f32 v79, v79, v80
	global_store_dwordx2 v[158:159], v[78:79], off
	v_cvt_pk_bf16_f32 v70, v70, v71
	v_mul_f32_e32 v71, v72, v198
	v_mul_f32_e32 v62, v62, v198
	v_mul_f32_e32 v63, v63, v198
	v_mul_f32_e32 v71, v92, v71
	v_mul_f32_e32 v72, v73, v198
	v_mul_f32_e32 v62, v86, v62
	v_mul_f32_e32 v63, v87, v63
	v_mul_f32_e32 v72, v93, v72
	v_cvt_pk_bf16_f32 v71, v71, v72
	global_store_dwordx2 v[158:159], v[70:71], off offset:512
	v_cvt_pk_bf16_f32 v62, v62, v63
	v_mul_f32_e32 v63, v64, v198
	v_mul_f32_e32 v54, v54, v198
	v_mul_f32_e32 v55, v55, v198
	v_mul_f32_e32 v63, v88, v63
	v_mul_f32_e32 v64, v65, v198
	v_mul_f32_e32 v54, v82, v54
	v_mul_f32_e32 v55, v83, v55
	v_mul_f32_e32 v64, v89, v64
	v_cvt_pk_bf16_f32 v63, v63, v64
	global_store_dwordx2 v[158:159], v[62:63], off offset:1024
	v_cvt_pk_bf16_f32 v54, v54, v55
	v_mul_f32_e32 v55, v56, v198
	v_mul_f32_e32 v50, v50, v198
	v_mul_f32_e32 v51, v51, v198
	v_mul_f32_e32 v55, v84, v55
	v_mul_f32_e32 v56, v57, v198
	v_mul_f32_e32 v50, v74, v50
	v_mul_f32_e32 v51, v75, v51
	v_mul_f32_e32 v56, v85, v56
	v_cvt_pk_bf16_f32 v55, v55, v56
	global_store_dwordx2 v[158:159], v[54:55], off offset:1536
	v_cvt_pk_bf16_f32 v50, v50, v51
	v_mul_f32_e32 v51, v52, v198
	v_mul_f32_e32 v42, v42, v198
	v_mul_f32_e32 v43, v43, v198
	v_mul_f32_e32 v51, v76, v51
	v_mul_f32_e32 v52, v53, v198
	v_mul_f32_e32 v42, v66, v42
	v_mul_f32_e32 v43, v67, v43
	v_mul_f32_e32 v52, v77, v52
	v_cvt_pk_bf16_f32 v51, v51, v52
	global_store_dwordx2 v[158:159], v[50:51], off offset:2048
	v_cvt_pk_bf16_f32 v42, v42, v43
	v_mul_f32_e32 v43, v44, v198
	v_mul_f32_e32 v38, v38, v198
	v_mul_f32_e32 v39, v39, v198
	v_mul_f32_e32 v43, v68, v43
	v_mul_f32_e32 v44, v45, v198
	v_mul_f32_e32 v38, v58, v38
	v_mul_f32_e32 v39, v59, v39
	v_mul_f32_e32 v44, v69, v44
	v_cvt_pk_bf16_f32 v43, v43, v44
	global_store_dwordx2 v[158:159], v[42:43], off offset:2560
	v_cvt_pk_bf16_f32 v38, v38, v39
	v_mul_f32_e32 v39, v40, v198
	v_mul_f32_e32 v34, v34, v198
	v_mul_f32_e32 v35, v35, v198
	v_mul_f32_e32 v39, v60, v39
	v_mul_f32_e32 v40, v41, v198
	v_mul_f32_e32 v34, v46, v34
	v_mul_f32_e32 v35, v47, v35
	v_mul_f32_e32 v40, v61, v40
	v_cvt_pk_bf16_f32 v39, v39, v40
	global_store_dwordx2 v[158:159], v[38:39], off offset:3072
	v_cvt_pk_bf16_f32 v34, v34, v35
	v_mul_f32_e32 v35, v36, v198
	v_mul_f32_e32 v30, v30, v198
	v_mul_f32_e32 v31, v31, v198
	v_mul_f32_e32 v35, v48, v35
	v_mul_f32_e32 v36, v37, v198
	s_waitcnt vmcnt(14)
	v_mul_f32_e32 v30, v166, v30
	v_mul_f32_e32 v31, v167, v31
	v_mul_f32_e32 v36, v49, v36
	v_cvt_pk_bf16_f32 v35, v35, v36
	global_store_dwordx2 v[158:159], v[34:35], off offset:3584
	v_cvt_pk_bf16_f32 v30, v30, v31
	v_mul_f32_e32 v31, v32, v198
	v_mul_f32_e32 v32, v33, v198
	v_mul_f32_e32 v31, v168, v31
	v_mul_f32_e32 v32, v169, v32
	v_cvt_pk_bf16_f32 v31, v31, v32
	v_add_co_u32_e32 v32, vcc, s13, v158
	v_mul_f32_e32 v26, v26, v198
	v_mul_f32_e32 v27, v27, v198
	v_addc_co_u32_e32 v33, vcc, 0, v159, vcc
	s_waitcnt vmcnt(14)
	v_mul_f32_e32 v26, v170, v26
	v_mul_f32_e32 v27, v171, v27
	global_store_dwordx2 v[32:33], v[30:31], off
	v_cvt_pk_bf16_f32 v26, v26, v27
	v_mul_f32_e32 v27, v28, v198
	v_mul_f32_e32 v18, v18, v198
	v_mul_f32_e32 v19, v19, v198
	v_mul_f32_e32 v27, v172, v27
	v_mul_f32_e32 v28, v29, v198
	s_waitcnt vmcnt(14)
	v_mul_f32_e32 v18, v174, v18
	v_mul_f32_e32 v19, v175, v19
	v_mul_f32_e32 v28, v173, v28
	v_cvt_pk_bf16_f32 v27, v27, v28
	global_store_dwordx2 v[32:33], v[26:27], off offset:512
	v_cvt_pk_bf16_f32 v18, v18, v19
	v_mul_f32_e32 v19, v20, v198
	v_mul_f32_e32 v19, v176, v19
	v_mul_f32_e32 v20, v21, v198
	v_mul_f32_e32 v20, v177, v20
	v_cvt_pk_bf16_f32 v19, v19, v20
	global_store_dwordx2 v[32:33], v[18:19], off offset:1024
	v_mul_f32_e32 v18, v22, v198
	v_mul_f32_e32 v19, v23, v198
	s_waitcnt vmcnt(15)
	v_mul_f32_e32 v18, v178, v18
	v_mul_f32_e32 v19, v179, v19
	v_cvt_pk_bf16_f32 v18, v18, v19
	v_mul_f32_e32 v19, v24, v198
	v_mul_f32_e32 v14, v14, v198
	v_mul_f32_e32 v15, v15, v198
	v_mul_f32_e32 v19, v180, v19
	v_mul_f32_e32 v20, v25, v198
	s_waitcnt vmcnt(14)
	v_mul_f32_e32 v14, v182, v14
	v_mul_f32_e32 v15, v183, v15
	v_mul_f32_e32 v20, v181, v20
	v_cvt_pk_bf16_f32 v19, v19, v20
	global_store_dwordx2 v[32:33], v[18:19], off offset:1536
	v_cvt_pk_bf16_f32 v14, v14, v15
	v_mul_f32_e32 v15, v16, v198
	v_mul_f32_e32 v10, v10, v198
	v_mul_f32_e32 v11, v11, v198
	v_mul_f32_e32 v15, v184, v15
	v_mul_f32_e32 v16, v17, v198
	s_waitcnt vmcnt(14)
	v_mul_f32_e32 v10, v186, v10
	v_mul_f32_e32 v11, v187, v11
	v_mul_f32_e32 v16, v185, v16
	v_cvt_pk_bf16_f32 v15, v15, v16
	global_store_dwordx2 v[32:33], v[14:15], off offset:2048
	v_cvt_pk_bf16_f32 v10, v10, v11
	v_mul_f32_e32 v11, v12, v198
	v_mul_f32_e32 v6, v6, v198
	v_mul_f32_e32 v7, v7, v198
	v_mul_f32_e32 v11, v188, v11
	v_mul_f32_e32 v12, v13, v198
	s_waitcnt vmcnt(14)
	v_mul_f32_e32 v6, v190, v6
	v_mul_f32_e32 v7, v191, v7
	v_mul_f32_e32 v12, v189, v12
	v_cvt_pk_bf16_f32 v11, v11, v12
	global_store_dwordx2 v[32:33], v[10:11], off offset:2560
	v_cvt_pk_bf16_f32 v6, v6, v7
	v_mul_f32_e32 v7, v8, v198
	v_mul_f32_e32 v2, v2, v198
	v_mul_f32_e32 v3, v3, v198
	v_mul_f32_e32 v7, v192, v7
	v_mul_f32_e32 v8, v9, v198
	s_waitcnt vmcnt(14)
	v_mul_f32_e32 v2, v194, v2
	v_mul_f32_e32 v3, v195, v3
	v_mul_f32_e32 v8, v193, v8
	v_cvt_pk_bf16_f32 v7, v7, v8
	global_store_dwordx2 v[32:33], v[6:7], off offset:3072
	v_cvt_pk_bf16_f32 v2, v2, v3
	v_mul_f32_e32 v3, v4, v198
	v_mul_f32_e32 v3, v196, v3
	v_mul_f32_e32 v4, v5, v198
	v_mul_f32_e32 v4, v197, v4
	v_cvt_pk_bf16_f32 v3, v3, v4

; #define GAS __attribute__((address_space(1)))
; __device__ __forceinline__ void rms_row_to_bf16(const float* xrow, const float* g, bf16_t* orow, int lane) {
;     const GAS f32x4* xr = (const GAS f32x4*)xrow + lane;
;     f32x4 v[16], gv[16]; float s = 0.f;
;     const GAS f32x4* gr = (const GAS f32x4*)g + lane;
; #pragma unroll
;     for (int j = 0; j < 16; ++j) v[j] = __builtin_nontemporal_load(xr + 64 * j);
; #pragma unroll
;     for (int j = 0; j < 16; ++j) gv[j] = gr[64 * j];
; #pragma unroll
;     for (int j = 0; j < 16; ++j) s += (v[j].x * v[j].x + v[j].y * v[j].y) + (v[j].z * v[j].z + v[j].w * v[j].w);
.LBB0_52:
	s_andn2_b64 vcc, exec, s[4:5]
	s_cbranch_vccnz .LBB0_45
	global_load_dwordx4 v[70:73], v[156:157], off nt
	global_load_dwordx4 v[62:65], v[156:157], off offset:1024 nt
	global_load_dwordx4 v[54:57], v[156:157], off offset:2048 nt
	global_load_dwordx4 v[50:53], v[156:157], off offset:3072 nt
	v_add_co_u32_e32 v2, vcc, 0x1000, v156
	s_nop 1

; __device__ __forceinline__ void rms_row_to_bf16(const float* xrow, const float* g, bf16_t* orow, int lane) {
;     ...
;     for (int j = 0; j < 16; ++j) v[j] = __builtin_nontemporal_load(xr + 64 * j);
; #pragma unroll
;     for (int j = 0; j < 16; ++j) gv[j] = gr[64 * j];
; #pragma unroll
;     for (int j = 0; j < 16; ++j) s += (v[j].x * v[j].x + v[j].y * v[j].y) + (v[j].z * v[j].z + v[j].w * v[j].w);
	v_addc_co_u32_e32 v3, vcc, 0, v157, vcc
	global_load_dwordx4 v[46:49], v[2:3], off nt
	global_load_dwordx4 v[42:45], v[2:3], off offset:1024 nt
	global_load_dwordx4 v[38:41], v[2:3], off offset:2048 nt
	global_load_dwordx4 v[34:37], v[2:3], off offset:3072 nt
	v_add_co_u32_e32 v2, vcc, 0x2000, v156
	s_nop 0
	s_nop 0
	v_addc_co_u32_e32 v3, vcc, 0, v157, vcc
	global_load_dwordx4 v[30:33], v[2:3], off nt
	global_load_dwordx4 v[26:29], v[2:3], off offset:1024 nt
	global_load_dwordx4 v[22:25], v[2:3], off offset:2048 nt
	global_load_dwordx4 v[18:21], v[2:3], off offset:3072 nt
	v_add_co_u32_e32 v2, vcc, 0x3000, v156
	s_nop 1

; #define GAS __attribute__((address_space(1)))
; __device__ __forceinline__ unsigned cvt_pk_bf16(float lo, float hi) { unsigned r; asm volatile("v_cvt_pk_bf16_f32 %0, %1, %2" : "=v"(r) : "v"(lo), "v"(hi)); return r; }
; __device__ __forceinline__ void rms_row_to_bf16(const float* xrow, const float* g, bf16_t* orow, int lane) {
;     ...
;     for (int j = 0; j < 16; ++j) v[j] = __builtin_nontemporal_load(xr + 64 * j);
; #pragma unroll
;     for (int j = 0; j < 16; ++j) gv[j] = gr[64 * j];
; #pragma unroll
;     for (int j = 0; j < 16; ++j) s += (v[j].x * v[j].x + v[j].y * v[j].y) + (v[j].z * v[j].z + v[j].w * v[j].w);
;     const float rstd = 1.0f / sqrtf(wave_sum(s) * (1.0f / DM) + EPS);
;     GAS u32x2* o8 = (GAS u32x2*)orow + lane;
; #pragma unroll
;     for (int j = 0; j < 16; ++j) { const f32x4 gg = gv[j]; u32x2 w; w.x = cvt_pk_bf16(v[j].x * rstd * gg.x, v[j].y * rstd * gg.y); w.y = cvt_pk_bf16(v[j].z * rstd * gg.z, v[j].w * rstd * gg.w); o8[64 * j] = w; }
	v_addc_co_u32_e32 v3, vcc, 0, v157, vcc
	global_load_dwordx4 v[14:17], v[2:3], off nt
	global_load_dwordx4 v[78:81], v[120:121], off
	global_load_dwordx4 v[74:77], v[120:121], off offset:1024
	global_load_dwordx4 v[66:69], v[120:121], off offset:2048
	global_load_dwordx4 v[58:61], v[120:121], off offset:3072
	global_load_dwordx4 v[10:13], v[2:3], off offset:1024 nt
	global_load_dwordx4 v[6:9], v[2:3], off offset:2048 nt
	s_nop 0
	global_load_dwordx4 v[2:5], v[2:3], off offset:3072 nt
	s_waitcnt vmcnt(19)
	v_mul_f32_e32 v82, v71, v71
	v_mul_f32_e32 v83, v73, v73
	s_waitcnt vmcnt(18)
	v_mul_f32_e32 v84, v63, v63
	v_mul_f32_e32 v85, v65, v65
	s_waitcnt vmcnt(17)
	v_mul_f32_e32 v86, v55, v55
	v_mul_f32_e32 v87, v57, v57
	v_fmac_f32_e32 v82, v70, v70
	v_fmac_f32_e32 v83, v72, v72
	v_fmac_f32_e32 v84, v62, v62
	v_fmac_f32_e32 v85, v64, v64
	s_waitcnt vmcnt(16)
	v_mul_f32_e32 v88, v51, v51
	v_mul_f32_e32 v89, v53, v53
	v_fmac_f32_e32 v86, v54, v54
	v_fmac_f32_e32 v87, v56, v56
	v_add_f32_e32 v82, v82, v83
	v_add_f32_e32 v83, v84, v85
	v_fmac_f32_e32 v88, v50, v50
	v_fmac_f32_e32 v89, v52, v52
	v_add_f32_e32 v84, v86, v87
	v_add_f32_e32 v82, v82, v83
	v_add_f32_e32 v85, v88, v89
	v_add_f32_e32 v82, v82, v84
	v_add_f32_e32 v82, v82, v85
	s_waitcnt vmcnt(15)
	v_mul_f32_e32 v86, v47, v47
	v_mul_f32_e32 v87, v49, v49
	s_waitcnt vmcnt(14)
	v_mul_f32_e32 v88, v43, v43
	v_mul_f32_e32 v89, v45, v45
	v_fmac_f32_e32 v86, v46, v46
	v_fmac_f32_e32 v87, v48, v48
	s_waitcnt vmcnt(13)
	v_mul_f32_e32 v90, v39, v39
	v_mul_f32_e32 v91, v41, v41
	v_fmac_f32_e32 v88, v42, v42
	v_fmac_f32_e32 v89, v44, v44
	v_add_f32_e32 v84, v86, v87
	s_waitcnt vmcnt(12)
	v_mul_f32_e32 v92, v35, v35
	v_mul_f32_e32 v93, v37, v37
	v_fmac_f32_e32 v90, v38, v38
	v_fmac_f32_e32 v91, v40, v40
	v_add_f32_e32 v86, v88, v89
	v_add_f32_e32 v82, v82, v84
	v_fmac_f32_e32 v92, v34, v34
	v_fmac_f32_e32 v93, v36, v36
	s_waitcnt vmcnt(11)
	v_mul_f32_e32 v83, v31, v31
	v_mul_f32_e32 v158, v33, v33
	v_add_f32_e32 v87, v90, v91
	v_add_f32_e32 v82, v82, v86
	s_waitcnt vmcnt(10)
	v_mul_f32_e32 v159, v27, v27
	v_mul_f32_e32 v162, v29, v29
	v_add_f32_e32 v88, v92, v93
	v_fmac_f32_e32 v83, v30, v30
	v_fmac_f32_e32 v158, v32, v32
	v_add_f32_e32 v82, v82, v87
	v_fmac_f32_e32 v159, v26, v26
	v_add_f32_e32 v83, v83, v158
	v_add_f32_e32 v82, v82, v88
	v_fmac_f32_e32 v162, v28, v28
	v_add_f32_e32 v82, v82, v83
	v_add_f32_e32 v83, v159, v162
	v_add_f32_e32 v82, v82, v83
	s_waitcnt vmcnt(9)
	v_mul_f32_e32 v83, v23, v23
	v_mul_f32_e32 v84, v25, v25
	v_fmac_f32_e32 v83, v22, v22
	v_fmac_f32_e32 v84, v24, v24
	v_add_f32_e32 v83, v83, v84
	v_add_f32_e32 v82, v82, v83
	s_waitcnt vmcnt(8)
	v_mul_f32_e32 v83, v19, v19
	v_mul_f32_e32 v84, v21, v21
	v_fmac_f32_e32 v83, v18, v18
	v_fmac_f32_e32 v84, v20, v20
	v_add_f32_e32 v83, v83, v84
	v_add_f32_e32 v82, v82, v83
	s_waitcnt vmcnt(7)
	v_mul_f32_e32 v83, v15, v15
	v_mul_f32_e32 v84, v17, v17
	v_fmac_f32_e32 v83, v14, v14
	v_fmac_f32_e32 v84, v16, v16
	v_add_f32_e32 v83, v83, v84
	v_add_f32_e32 v82, v82, v83
	s_waitcnt vmcnt(2)
	v_mul_f32_e32 v83, v11, v11
	v_mul_f32_e32 v84, v13, v13
	v_fmac_f32_e32 v83, v10, v10
	v_fmac_f32_e32 v84, v12, v12
	v_add_f32_e32 v83, v83, v84
	v_add_f32_e32 v82, v82, v83
	s_waitcnt vmcnt(1)
	v_mul_f32_e32 v83, v7, v7
	v_mul_f32_e32 v84, v9, v9
	v_fmac_f32_e32 v83, v6, v6
	v_fmac_f32_e32 v84, v8, v8
	v_add_f32_e32 v83, v83, v84
	v_add_f32_e32 v82, v82, v83
	s_waitcnt vmcnt(0)
	v_mul_f32_e32 v83, v3, v3
	v_mul_f32_e32 v84, v5, v5
	v_fmac_f32_e32 v83, v2, v2
	v_fmac_f32_e32 v84, v4, v4
	v_add_f32_e32 v83, v83, v84
	v_add_f32_e32 v82, v82, v83
	v_mov_b32_e32 v83, 0
	s_nop 0
	v_add_f32_dpp v82, v82, v82 quad_perm:[1,0,3,2] row_mask:0xf bank_mask:0xf bound_ctrl:1
	s_nop 1
	v_add_f32_dpp v82, v82, v82 quad_perm:[2,3,0,1] row_mask:0xf bank_mask:0xf bound_ctrl:1
	s_nop 1
	v_add_f32_dpp v82, v82, v82 row_half_mirror row_mask:0xf bank_mask:0xf bound_ctrl:1
	s_nop 1
	v_add_f32_dpp v82, v82, v82 row_mirror row_mask:0xf bank_mask:0xf bound_ctrl:1
	s_nop 1
	v_mov_b32_dpp v83, v82 row_bcast:15 row_mask:0xa bank_mask:0xf
	v_add_f32_e32 v82, v82, v83
	v_mov_b32_e32 v83, 0
	s_nop 1
	v_mov_b32_dpp v83, v82 row_bcast:31 row_mask:0xc bank_mask:0xf
	v_add_f32_e32 v86, v82, v83
	global_load_dwordx4 v[82:85], v[122:123], off
	v_readlane_b32 s4, v86, 63
	s_nop 1
	v_fma_f32 v86, s4, v161, v1
	v_mul_f32_e32 v87, 0x4f800000, v86
	v_cmp_gt_f32_e32 vcc, s18, v86
	s_nop 1
	v_cndmask_b32_e32 v86, v86, v87, vcc
	v_sqrt_f32_e32 v87, v86
	s_nop 0
	v_add_u32_e32 v88, -1, v87
	v_fma_f32 v89, -v88, v87, v86
	v_cmp_ge_f32_e64 s[4:5], 0, v89
	v_add_u32_e32 v89, 1, v87
	s_nop 0
	v_cndmask_b32_e64 v88, v87, v88, s[4:5]
	v_fma_f32 v87, -v89, v87, v86
	v_cmp_lt_f32_e64 s[4:5], 0, v87
	s_nop 1
	v_cndmask_b32_e64 v87, v88, v89, s[4:5]
	v_mul_f32_e32 v88, 0x37800000, v87
	v_cndmask_b32_e32 v87, v87, v88, vcc
	v_cmp_class_f32_e32 vcc, v86, v160
	s_nop 1
	v_cndmask_b32_e32 v158, v87, v86, vcc
	v_div_scale_f32 v90, s[4:5], v158, v158, 1.0
	v_rcp_f32_e32 v159, v90
	global_load_dwordx4 v[86:89], v[124:125], off
	v_fma_f32 v91, -v90, v159, 1.0
	v_fmac_f32_e32 v159, v91, v159
	v_div_scale_f32 v91, vcc, 1.0, v158, 1.0
	v_mul_f32_e32 v162, v91, v159
	v_fma_f32 v92, -v90, v162, v91
	v_fmac_f32_e32 v162, v92, v159
	v_fma_f32 v163, -v90, v162, v91
	v_div_fmas_f32 v159, v163, v159, v162
	global_load_dwordx4 v[90:93], v[126:127], off
	v_div_fixup_f32 v158, v159, v158, 1.0
	v_mul_f32_e32 v70, v70, v158
	v_mul_f32_e32 v71, v71, v158
	v_mul_f32_e32 v72, v72, v158
	v_mul_f32_e32 v159, v73, v158
	v_mul_f32_e32 v78, v78, v70
	v_mul_f32_e32 v79, v79, v71
	v_mul_f32_e32 v80, v80, v72
	global_load_dwordx4 v[70:73], v[128:129], off
	v_mul_f32_e32 v62, v62, v158
	v_mul_f32_e32 v63, v63, v158
	v_mul_f32_e32 v64, v64, v158
	v_mul_f32_e32 v65, v65, v158
	v_mul_f32_e32 v81, v81, v159
	v_mul_f32_e32 v159, v74, v62
	v_mul_f32_e32 v162, v75, v63
	v_mul_f32_e32 v163, v76, v64
	v_mul_f32_e32 v164, v77, v65
	global_load_dwordx4 v[62:65], v[130:131], off
	v_mul_f32_e32 v54, v54, v158
	v_mul_f32_e32 v50, v50, v158
	v_mul_f32_e32 v51, v51, v158
	v_mul_f32_e32 v52, v52, v158
	v_mul_f32_e32 v165, v66, v54
	v_mul_f32_e32 v54, v53, v158
	v_mul_f32_e32 v169, v58, v50
	v_mul_f32_e32 v170, v59, v51
	v_mul_f32_e32 v171, v60, v52
	global_load_dwordx4 v[50:53], v[132:133], off
	v_mul_f32_e32 v46, v46, v158
	v_mul_f32_e32 v47, v47, v158
	v_mul_f32_e32 v48, v48, v158
	v_mul_f32_e32 v49, v49, v158
	s_waitcnt vmcnt(5)
; __device__ __forceinline__ unsigned cvt_pk_bf16(float lo, float hi) { unsigned r; asm volatile("v_cvt_pk_bf16_f32 %0, %1, %2" : "=v"(r) : "v"(lo), "v"(hi)); return r; }
; __device__ __forceinline__ void rms_row_to_bf16(const float* xrow, const float* g, bf16_t* orow, int lane) {
;     ...
; #pragma unroll
;     for (int j = 0; j < 16; ++j) { const f32x4 gg = gv[j]; u32x2 w; w.x = cvt_pk_bf16(v[j].x * rstd * gg.x, v[j].y * rstd * gg.y); w.y = cvt_pk_bf16(v[j].z * rstd * gg.z, v[j].w * rstd * gg.w); o8[64 * j] = w; }
; }
	v_mul_f32_e32 v82, v82, v46
	v_mul_f32_e32 v83, v83, v47
	v_mul_f32_e32 v84, v84, v48
	v_mul_f32_e32 v85, v85, v49
	global_load_dwordx4 v[46:49], v[134:135], off
	v_mul_f32_e32 v55, v55, v158
	v_mul_f32_e32 v56, v56, v158
	v_mul_f32_e32 v57, v57, v158
	v_mul_f32_e32 v166, v67, v55
	v_mul_f32_e32 v167, v68, v56
	v_mul_f32_e32 v168, v69, v57
	v_mul_f32_e32 v172, v61, v54
	v_mul_f32_e32 v173, v42, v158
	v_mul_f32_e32 v174, v43, v158
	v_mul_f32_e32 v175, v44, v158
	v_mul_f32_e32 v176, v45, v158
	global_load_dwordx4 v[42:45], v[136:137], off
	global_load_dwordx4 v[54:57], v[138:139], off
	global_load_dwordx4 v[58:61], v[140:141], off
	global_load_dwordx4 v[66:69], v[142:143], off
	global_load_dwordx4 v[74:77], v[144:145], off
	v_cvt_pk_bf16_f32 v78, v78, v79
	v_cvt_pk_bf16_f32 v79, v80, v81
	global_store_dwordx2 v[154:155], v[78:79], off
	v_cvt_pk_bf16_f32 v78, v159, v162
	v_cvt_pk_bf16_f32 v79, v163, v164
	global_store_dwordx2 v[154:155], v[78:79], off offset:512
	v_cvt_pk_bf16_f32 v78, v165, v166
	v_cvt_pk_bf16_f32 v79, v167, v168
	global_store_dwordx2 v[154:155], v[78:79], off offset:1024
	v_cvt_pk_bf16_f32 v78, v169, v170
	v_cvt_pk_bf16_f32 v79, v171, v172
	global_store_dwordx2 v[154:155], v[78:79], off offset:1536
	v_cvt_pk_bf16_f32 v78, v82, v83
	v_cvt_pk_bf16_f32 v79, v84, v85
	global_store_dwordx2 v[154:155], v[78:79], off offset:2048
	v_mul_f32_e32 v38, v38, v158
	v_mul_f32_e32 v39, v39, v158
	s_waitcnt vmcnt(15)
	v_mul_f32_e32 v78, v86, v173
	v_mul_f32_e32 v79, v87, v174
	v_cvt_pk_bf16_f32 v78, v78, v79
	v_mul_f32_e32 v79, v88, v175
	v_mul_f32_e32 v80, v89, v176
	v_cvt_pk_bf16_f32 v79, v79, v80
	global_store_dwordx2 v[154:155], v[78:79], off offset:2560
	v_mul_f32_e32 v34, v34, v158
	v_mul_f32_e32 v35, v35, v158
	v_mul_f32_e32 v30, v30, v158
	v_mul_f32_e32 v31, v31, v158
	v_mul_f32_e32 v26, v26, v158
	s_waitcnt vmcnt(15)
	v_mul_f32_e32 v38, v90, v38
	v_mul_f32_e32 v39, v91, v39
	v_cvt_pk_bf16_f32 v38, v38, v39
	v_mul_f32_e32 v39, v40, v158
	v_mul_f32_e32 v39, v92, v39
	v_mul_f32_e32 v40, v41, v158
	v_mul_f32_e32 v40, v93, v40
	v_cvt_pk_bf16_f32 v39, v39, v40
	global_store_dwordx2 v[154:155], v[38:39], off offset:3072
	s_waitcnt vmcnt(15)
	v_mul_f32_e32 v34, v70, v34
	v_mul_f32_e32 v35, v71, v35
	v_cvt_pk_bf16_f32 v34, v34, v35
	v_mul_f32_e32 v35, v36, v158
	v_mul_f32_e32 v35, v72, v35
	v_mul_f32_e32 v36, v37, v158
	v_mul_f32_e32 v36, v73, v36
	v_cvt_pk_bf16_f32 v35, v35, v36
	global_store_dwordx2 v[154:155], v[34:35], off offset:3584
	v_mul_f32_e32 v27, v27, v158
	s_waitcnt vmcnt(15)
	v_mul_f32_e32 v30, v62, v30
	v_mul_f32_e32 v31, v63, v31
	v_cvt_pk_bf16_f32 v30, v30, v31
	v_mul_f32_e32 v31, v32, v158
	v_mul_f32_e32 v32, v33, v158
	v_mul_f32_e32 v31, v64, v31
	v_mul_f32_e32 v32, v65, v32
	v_cvt_pk_bf16_f32 v31, v31, v32
	v_add_co_u32_e32 v32, vcc, s13, v154
	s_waitcnt vmcnt(14)
	v_mul_f32_e32 v26, v50, v26
	v_addc_co_u32_e32 v33, vcc, 0, v155, vcc
	v_mul_f32_e32 v27, v51, v27
	global_store_dwordx2 v[32:33], v[30:31], off
	v_cvt_pk_bf16_f32 v26, v26, v27
	v_mul_f32_e32 v27, v28, v158
	v_mul_f32_e32 v22, v22, v158
	v_mul_f32_e32 v23, v23, v158
	v_mul_f32_e32 v27, v52, v27
	v_mul_f32_e32 v28, v29, v158
	s_waitcnt vmcnt(14)
	v_mul_f32_e32 v22, v46, v22
	v_mul_f32_e32 v23, v47, v23
	v_mul_f32_e32 v28, v53, v28
	v_cvt_pk_bf16_f32 v27, v27, v28
	global_store_dwordx2 v[32:33], v[26:27], off offset:512
	v_cvt_pk_bf16_f32 v22, v22, v23
	v_mul_f32_e32 v23, v24, v158
	v_mul_f32_e32 v18, v18, v158
	v_mul_f32_e32 v19, v19, v158
	v_mul_f32_e32 v23, v48, v23
	v_mul_f32_e32 v24, v25, v158
	s_waitcnt vmcnt(14)
	v_mul_f32_e32 v18, v42, v18
	v_mul_f32_e32 v19, v43, v19
	v_mul_f32_e32 v24, v49, v24
	v_cvt_pk_bf16_f32 v23, v23, v24
	global_store_dwordx2 v[32:33], v[22:23], off offset:1024
	v_cvt_pk_bf16_f32 v18, v18, v19
	v_mul_f32_e32 v19, v20, v158
	v_mul_f32_e32 v14, v14, v158
	v_mul_f32_e32 v15, v15, v158
	v_mul_f32_e32 v19, v44, v19
	v_mul_f32_e32 v20, v21, v158
	s_waitcnt vmcnt(14)
	v_mul_f32_e32 v14, v54, v14
	v_mul_f32_e32 v15, v55, v15
	v_mul_f32_e32 v20, v45, v20
	v_cvt_pk_bf16_f32 v19, v19, v20
	global_store_dwordx2 v[32:33], v[18:19], off offset:1536
	v_cvt_pk_bf16_f32 v14, v14, v15
	v_mul_f32_e32 v15, v16, v158
	v_mul_f32_e32 v10, v10, v158
	v_mul_f32_e32 v11, v11, v158
	v_mul_f32_e32 v15, v56, v15
	v_mul_f32_e32 v16, v17, v158
	s_waitcnt vmcnt(14)
	v_mul_f32_e32 v10, v58, v10
	v_mul_f32_e32 v11, v59, v11
	v_mul_f32_e32 v16, v57, v16
	v_cvt_pk_bf16_f32 v15, v15, v16
	global_store_dwordx2 v[32:33], v[14:15], off offset:2048
	v_cvt_pk_bf16_f32 v10, v10, v11
	v_mul_f32_e32 v11, v12, v158
	v_mul_f32_e32 v6, v6, v158
	v_mul_f32_e32 v7, v7, v158
	v_mul_f32_e32 v11, v60, v11
	v_mul_f32_e32 v12, v13, v158
	s_waitcnt vmcnt(14)
	v_mul_f32_e32 v6, v66, v6
	v_mul_f32_e32 v7, v67, v7
	v_mul_f32_e32 v12, v61, v12
	v_cvt_pk_bf16_f32 v11, v11, v12
	global_store_dwordx2 v[32:33], v[10:11], off offset:2560
	v_cvt_pk_bf16_f32 v6, v6, v7
	v_mul_f32_e32 v7, v8, v158
	v_mul_f32_e32 v2, v2, v158
	v_mul_f32_e32 v3, v3, v158
	v_mul_f32_e32 v7, v68, v7
	v_mul_f32_e32 v8, v9, v158
	s_waitcnt vmcnt(14)
	v_mul_f32_e32 v2, v74, v2
	v_mul_f32_e32 v3, v75, v3
	v_mul_f32_e32 v8, v69, v8
	v_cvt_pk_bf16_f32 v7, v7, v8
	global_store_dwordx2 v[32:33], v[6:7], off offset:3072
	v_cvt_pk_bf16_f32 v2, v2, v3
	v_mul_f32_e32 v3, v4, v158
	v_mul_f32_e32 v3, v76, v3
	v_mul_f32_e32 v4, v5, v158
	v_mov_b64_e32 v[158:159], v[154:155]
	v_mul_f32_e32 v4, v77, v4
	v_cvt_pk_bf16_f32 v3, v3, v4
	s_branch .LBB0_45
